# NSA selected loop: 6 of 8 K fragments also shared across a tile's column groups
# speedup vs baseline: 1.0337x; 1.0013x over previous
; #define LAS __attribute__((address_space(3)))
; #define MFMA16(a, b, c) __builtin_amdgcn_mfma_f32_16x16x32_bf16((a), (b), (c), 0, 0, 0)
; __device__ __forceinline__ void sel_group(const LAS bf16_t* Kt, const LAS bf16_t* Vt, LAS float* S, const bf16x8 qB0, const bf16x8 qB1, int jc, int rc, bool valid, bool masked, int tw64, int lr, int q) {
;     LAS float* Srow = S + (jc * 3 + rc) * 68;
;     const float mref = Srow[65]; const bool st = Srow[66] != 0.f;
;     f32x4 acc[4];
; #pragma unroll
;     for (int dt = 0; dt < 4; ++dt) acc[dt] = *(const LAS f32x4*)(Srow + 16 * dt + 4 * q);
;     float lc = Srow[64];
;     const float nm = valid ? -mref : -1e30f;
;     const f32x4 c0 = (f32x4){nm, nm, nm, nm};
;     const LAS bf16_t* kbase = Kt + lr * 72 + 8 * q;
;     f32x4 s[4];
;     {
;         bf16x8 kf[2][2];
;         kf[0][0] = *(const LAS bf16x8*)(kbase); kf[0][1] = *(const LAS bf16x8*)(kbase + 32);
; #pragma unroll
;         for (int mt = 0; mt < 4; ++mt) {
;             if (mt < 3) { kf[(mt + 1) & 1][0] = *(const LAS bf16x8*)(kbase + 16 * (mt + 1) * 72); kf[(mt + 1) & 1][1] = *(const LAS bf16x8*)(kbase + 16 * (mt + 1) * 72 + 32); }
;             __builtin_amdgcn_sched_barrier(0);
;             __builtin_amdgcn_s_setprio(1); s[mt] = MFMA16(kf[mt & 1][0], qB0, c0); s[mt] = MFMA16(kf[mt & 1][1], qB1, s[mt]); __builtin_amdgcn_s_setprio(0);
;             __builtin_amdgcn_sched_barrier(0);
;         }
;     }
;     if (masked) {
;         const int hq = tw64 + jc - 4 * q;
; #pragma unroll
;         for (int mt = 0; mt < 4; ++mt)
; #pragma unroll
;             for (int i = 0; i < 4; ++i) s[mt][i] = ((16 * mt + i) <= hq) ? s[mt][i] : -1e30f;
; __device__ __forceinline__ void nsa_phase(LAS unsigned char* lds, const bf16_t* Q, const bf16_t* KVG, size_t kvg_stride, const bf16_t* kcc, const bf16_t* vcc, const float* G, bf16_t* cat,
;                                           int tid, int lane, int wave) {
;     ...
;                     __syncthreads();
;                     const int ng = (3 * ksel + 15) >> 4;
;                     const bool msk = (n == ((t0 + 16 * wave) >> 6));
; #pragma unroll
;                     for (int gi = 0; gi < 3; ++gi)
;                         if (gi < ng) sel_group(Kt, Vt, Ssel, qB[gi][0], qB[gi][1], jcg[gi], rcg[gi], vg[gi], msk, t0 + 16 * wave - 64 * n, lr, q);
.Lsp_gdone_loop:
	s_waitcnt lgkmcnt(0)
	s_cmp_eq_u32 s101, 1
	s_cselect_b64 s[2:3], -1, 0
	s_cmp_eq_u32 s45, s38
	s_cselect_b64 s[12:13], -1, 0
	v_add_u32_e32 v48, s6, v99
	v_add_u32_e32 v117, v48, v97
	v_cndmask_b32_e64 v48, 0, 1, s[12:13]
	v_add3_u32 v115, s6, v104, v114
	s_cmp_eq_u32 s10, 0
	v_cmp_ne_u32_e64 s[72:73], 1, v48
	s_barrier
	s_cbranch_scc1 .LBB0_1078
	v_mad_u64_u32 v[48:49], s[4:5], v120, 3, v[88:89]
	v_mul_lo_u32 v48, v48, s36
	v_add_u32_e32 v119, s49, v48
	v_add_u32_e32 v48, v119, v97
	ds_read_b96 v[84:86], v119 offset:46336
	ds_read_b128 v[60:63], v48 offset:46080
	ds_read_b128 v[56:59], v48 offset:46144
	ds_read_b128 v[52:55], v48 offset:46208
	ds_read_b128 v[48:51], v48 offset:46272
	ds_read_b128 v[174:177], v117
	ds_read_b128 v[178:181], v117 offset:64
	ds_read_b128 v[182:185], v117 offset:2304
	ds_read_b128 v[186:189], v117 offset:2368
	s_waitcnt lgkmcnt(8)
	v_cndmask_b32_e64 v126, v222, -v85, s[76:77]
	v_mov_b32_e32 v127, v126
	v_mov_b32_e32 v128, v126
	v_mov_b32_e32 v129, v126
	s_setprio 1
	s_waitcnt lgkmcnt(3)
	v_mfma_f32_16x16x32_bf16 v[64:67], v[174:177], v[76:79], v[126:129]
	s_waitcnt lgkmcnt(2)
	v_mfma_f32_16x16x32_bf16 v[64:67], v[178:181], v[80:83], v[64:67]
	s_setprio 0
	ds_read_b128 v[200:203], v117 offset:4608
	ds_read_b128 v[216:219], v117 offset:4672
	s_setprio 1
	s_waitcnt lgkmcnt(3)
	v_mfma_f32_16x16x32_bf16 v[68:71], v[182:185], v[76:79], v[126:129]
	s_waitcnt lgkmcnt(2)
	v_mfma_f32_16x16x32_bf16 v[68:71], v[186:189], v[80:83], v[68:71]
	s_setprio 0
	ds_read_b128 v[122:125], v117 offset:6912
	ds_read_b128 v[138:141], v117 offset:6976
	s_setprio 1
	s_waitcnt lgkmcnt(3)
	v_mfma_f32_16x16x32_bf16 v[72:75], v[200:203], v[76:79], v[126:129]
	s_waitcnt lgkmcnt(2)
	v_mfma_f32_16x16x32_bf16 v[72:75], v[216:219], v[80:83], v[72:75]
	s_setprio 0
	s_setprio 1
	s_waitcnt lgkmcnt(1)
	v_mfma_f32_16x16x32_bf16 v[76:79], v[122:125], v[76:79], v[126:129]
	s_waitcnt lgkmcnt(0)
	v_mfma_f32_16x16x32_bf16 v[76:79], v[138:141], v[80:83], v[76:79]
	s_setprio 0
	s_and_b64 vcc, exec, s[72:73]
	s_cbranch_vccnz .LBB0_1067
	v_add_u32_e32 v80, v120, v111
	v_cmp_lt_i32_e32 vcc, -1, v80
	s_nop 1
	v_cndmask_b32_e32 v64, v222, v64, vcc
	v_cmp_lt_i32_e32 vcc, 0, v80
	s_nop 1
	v_cndmask_b32_e32 v65, v222, v65, vcc
	v_cmp_lt_i32_e32 vcc, 1, v80
	s_nop 1
	v_cndmask_b32_e32 v66, v222, v66, vcc
	v_cmp_lt_i32_e32 vcc, 2, v80
	s_nop 1
	v_cndmask_b32_e32 v67, v222, v67, vcc
	v_cmp_lt_i32_e32 vcc, 15, v80
	s_nop 1
	v_cndmask_b32_e32 v68, v222, v68, vcc
	v_cmp_lt_i32_e32 vcc, 16, v80
	s_nop 1
	v_cndmask_b32_e32 v69, v222, v69, vcc
	v_cmp_lt_i32_e32 vcc, 17, v80
	s_nop 1
	v_cndmask_b32_e32 v70, v222, v70, vcc
	v_cmp_lt_i32_e32 vcc, 18, v80
	s_nop 1
	v_cndmask_b32_e32 v71, v222, v71, vcc
	v_cmp_lt_i32_e32 vcc, 31, v80
	s_nop 1
	v_cndmask_b32_e32 v72, v222, v72, vcc
	v_cmp_lt_i32_e32 vcc, 32, v80
	s_nop 1
	v_cndmask_b32_e32 v73, v222, v73, vcc
	v_cmp_lt_i32_e32 vcc, 33, v80
	s_nop 1
	v_cndmask_b32_e32 v74, v222, v74, vcc
	v_cmp_lt_i32_e32 vcc, 34, v80
	s_nop 1
	v_cndmask_b32_e32 v75, v222, v75, vcc
	v_cmp_lt_i32_e32 vcc, 47, v80
	s_nop 1
	v_cndmask_b32_e32 v76, v222, v76, vcc
	v_cmp_lt_i32_e32 vcc, 48, v80
	s_nop 1
	v_cndmask_b32_e32 v77, v222, v77, vcc
	v_cmp_lt_i32_e32 vcc, 49, v80
	s_nop 1
	v_cndmask_b32_e32 v78, v222, v78, vcc
	v_cmp_lt_i32_e32 vcc, 50, v80
	s_nop 1
	v_cndmask_b32_e32 v79, v222, v79, vcc

; #define LAS __attribute__((address_space(3)))
; #define MFMA16(a, b, c) __builtin_amdgcn_mfma_f32_16x16x32_bf16((a), (b), (c), 0, 0, 0)
; __device__ __forceinline__ void sel_group(const LAS bf16_t* Kt, const LAS bf16_t* Vt, LAS float* S, const bf16x8 qB0, const bf16x8 qB1, int jc, int rc, bool valid, bool masked, int tw64, int lr, int q) {
;     LAS float* Srow = S + (jc * 3 + rc) * 68;
;     const float mref = Srow[65]; const bool st = Srow[66] != 0.f;
;     f32x4 acc[4];
; #pragma unroll
;     for (int dt = 0; dt < 4; ++dt) acc[dt] = *(const LAS f32x4*)(Srow + 16 * dt + 4 * q);
;     float lc = Srow[64];
;     const float nm = valid ? -mref : -1e30f;
;     const f32x4 c0 = (f32x4){nm, nm, nm, nm};
;     const LAS bf16_t* kbase = Kt + lr * 72 + 8 * q;
;     f32x4 s[4];
;     {
;         bf16x8 kf[2][2];
;         kf[0][0] = *(const LAS bf16x8*)(kbase); kf[0][1] = *(const LAS bf16x8*)(kbase + 32);
; #pragma unroll
;         for (int mt = 0; mt < 4; ++mt) {
;             if (mt < 3) { kf[(mt + 1) & 1][0] = *(const LAS bf16x8*)(kbase + 16 * (mt + 1) * 72); kf[(mt + 1) & 1][1] = *(const LAS bf16x8*)(kbase + 16 * (mt + 1) * 72 + 32); }
;             __builtin_amdgcn_sched_barrier(0);
;             __builtin_amdgcn_s_setprio(1); s[mt] = MFMA16(kf[mt & 1][0], qB0, c0); s[mt] = MFMA16(kf[mt & 1][1], qB1, s[mt]); __builtin_amdgcn_s_setprio(0);
;             __builtin_amdgcn_sched_barrier(0);
;         }
.LBB0_1078:
	s_cmp_lt_u32 s10, 6
	s_cbranch_scc1 .LBB0_1092
	v_mad_u64_u32 v[48:49], s[4:5], v118, 3, v[92:93]
	v_mul_lo_u32 v48, v48, s36
	v_add_u32_e32 v79, s49, v48
	v_add_u32_e32 v48, v79, v97
	ds_read_b96 v[76:78], v79 offset:46336
	ds_read_b128 v[60:63], v48 offset:46080
	ds_read_b128 v[56:59], v48 offset:46144
	ds_read_b128 v[52:55], v48 offset:46208
	ds_read_b128 v[48:51], v48 offset:46272
	ds_read_b128 v[80:83], v117 offset:6912
	ds_read_b128 v[132:135], v117 offset:6976
	s_waitcnt lgkmcnt(6)
	v_cndmask_b32_e64 v120, v222, -v77, s[74:75]
	v_mov_b32_e32 v121, v120
	v_mov_b32_e32 v122, v120
	v_mov_b32_e32 v123, v120
	s_setprio 1
	s_nop 0
	v_mfma_f32_16x16x32_bf16 v[64:67], v[174:177], v[40:43], v[120:123]
	v_mfma_f32_16x16x32_bf16 v[64:67], v[178:181], v[44:47], v[64:67]
	v_mfma_f32_16x16x32_bf16 v[68:71], v[182:185], v[40:43], v[120:123]
	v_mfma_f32_16x16x32_bf16 v[68:71], v[186:189], v[44:47], v[68:71]
	v_mfma_f32_16x16x32_bf16 v[72:75], v[200:203], v[40:43], v[120:123]
	v_mfma_f32_16x16x32_bf16 v[72:75], v[216:219], v[44:47], v[72:75]
	s_waitcnt lgkmcnt(1)
	v_mfma_f32_16x16x32_bf16 v[40:43], v[80:83], v[40:43], v[120:123]
	s_waitcnt lgkmcnt(0)
	v_mfma_f32_16x16x32_bf16 v[40:43], v[132:135], v[44:47], v[40:43]
	s_setprio 0
	s_and_b64 vcc, exec, s[72:73]
	s_cbranch_vccnz .LBB0_1081
	v_add_u32_e32 v44, v118, v111
	v_cmp_lt_i32_e32 vcc, -1, v44
	s_nop 1
	v_cndmask_b32_e32 v64, v222, v64, vcc
	v_cmp_lt_i32_e32 vcc, 0, v44
	s_nop 1
	v_cndmask_b32_e32 v65, v222, v65, vcc
	v_cmp_lt_i32_e32 vcc, 1, v44
	s_nop 1
	v_cndmask_b32_e32 v66, v222, v66, vcc
	v_cmp_lt_i32_e32 vcc, 2, v44
	s_nop 1
	v_cndmask_b32_e32 v67, v222, v67, vcc
	v_cmp_lt_i32_e32 vcc, 15, v44
	s_nop 1
	v_cndmask_b32_e32 v68, v222, v68, vcc
	v_cmp_lt_i32_e32 vcc, 16, v44
	s_nop 1
	v_cndmask_b32_e32 v69, v222, v69, vcc
	v_cmp_lt_i32_e32 vcc, 17, v44
	s_nop 1
	v_cndmask_b32_e32 v70, v222, v70, vcc
	v_cmp_lt_i32_e32 vcc, 18, v44
	s_nop 1
	v_cndmask_b32_e32 v71, v222, v71, vcc
	v_cmp_lt_i32_e32 vcc, 31, v44
	s_nop 1
	v_cndmask_b32_e32 v72, v222, v72, vcc
	v_cmp_lt_i32_e32 vcc, 32, v44
	s_nop 1
	v_cndmask_b32_e32 v73, v222, v73, vcc
	v_cmp_lt_i32_e32 vcc, 33, v44
	s_nop 1
	v_cndmask_b32_e32 v74, v222, v74, vcc
	v_cmp_lt_i32_e32 vcc, 34, v44
	s_nop 1
	v_cndmask_b32_e32 v75, v222, v75, vcc
	v_cmp_lt_i32_e32 vcc, 47, v44
	s_nop 1
	v_cndmask_b32_e32 v40, v222, v40, vcc
	v_cmp_lt_i32_e32 vcc, 48, v44
	s_nop 1
	v_cndmask_b32_e32 v41, v222, v41, vcc
	v_cmp_lt_i32_e32 vcc, 49, v44
	s_nop 1
	v_cndmask_b32_e32 v42, v222, v42, vcc
	v_cmp_lt_i32_e32 vcc, 50, v44
	s_nop 1
	v_cndmask_b32_e32 v43, v222, v43, vcc

; #define LAS __attribute__((address_space(3)))
; #define MFMA16(a, b, c) __builtin_amdgcn_mfma_f32_16x16x32_bf16((a), (b), (c), 0, 0, 0)
; __device__ __forceinline__ void sel_group(const LAS bf16_t* Kt, const LAS bf16_t* Vt, LAS float* S, const bf16x8 qB0, const bf16x8 qB1, int jc, int rc, bool valid, bool masked, int tw64, int lr, int q) {
;     LAS float* Srow = S + (jc * 3 + rc) * 68;
;     const float mref = Srow[65]; const bool st = Srow[66] != 0.f;
;     f32x4 acc[4];
; #pragma unroll
;     for (int dt = 0; dt < 4; ++dt) acc[dt] = *(const LAS f32x4*)(Srow + 16 * dt + 4 * q);
;     float lc = Srow[64];
;     const float nm = valid ? -mref : -1e30f;
;     const f32x4 c0 = (f32x4){nm, nm, nm, nm};
;     const LAS bf16_t* kbase = Kt + lr * 72 + 8 * q;
;     f32x4 s[4];
;     {
;         bf16x8 kf[2][2];
;         kf[0][0] = *(const LAS bf16x8*)(kbase); kf[0][1] = *(const LAS bf16x8*)(kbase + 32);
; #pragma unroll
;         for (int mt = 0; mt < 4; ++mt) {
;             if (mt < 3) { kf[(mt + 1) & 1][0] = *(const LAS bf16x8*)(kbase + 16 * (mt + 1) * 72); kf[(mt + 1) & 1][1] = *(const LAS bf16x8*)(kbase + 16 * (mt + 1) * 72 + 32); }
;             __builtin_amdgcn_sched_barrier(0);
;             __builtin_amdgcn_s_setprio(1); s[mt] = MFMA16(kf[mt & 1][0], qB0, c0); s[mt] = MFMA16(kf[mt & 1][1], qB1, s[mt]); __builtin_amdgcn_s_setprio(0);
;             __builtin_amdgcn_sched_barrier(0);
;         }
.LBB0_1092:
	s_cmp_lt_u32 s10, 11
	s_cbranch_scc1 .LBB0_1057
	s_nop 0
	v_mad_u64_u32 v[40:41], s[4:5], v116, 3, v[96:97]
	v_mul_lo_u32 v40, v40, s36
	v_add_u32_e32 v71, s49, v40
	v_add_u32_e32 v40, v71, v97
	ds_read_b96 v[68:70], v71 offset:46336
	ds_read_b128 v[52:55], v40 offset:46080
	ds_read_b128 v[48:51], v40 offset:46144
	ds_read_b128 v[44:47], v40 offset:46208
	ds_read_b128 v[40:43], v40 offset:46272
	ds_read_b128 v[72:75], v117 offset:6912
	ds_read_b128 v[122:125], v117 offset:6976
	s_waitcnt lgkmcnt(6)
	v_cndmask_b32_e64 v76, v222, -v69, s[70:71]
	v_mov_b32_e32 v77, v76
	v_mov_b32_e32 v78, v76
	v_mov_b32_e32 v79, v76
	s_setprio 1
	s_nop 0
	v_mfma_f32_16x16x32_bf16 v[56:59], v[174:177], v[32:35], v[76:79]
	v_mfma_f32_16x16x32_bf16 v[56:59], v[178:181], v[36:39], v[56:59]
	v_mfma_f32_16x16x32_bf16 v[60:63], v[182:185], v[32:35], v[76:79]
	v_mfma_f32_16x16x32_bf16 v[60:63], v[186:189], v[36:39], v[60:63]
	v_mfma_f32_16x16x32_bf16 v[64:67], v[200:203], v[32:35], v[76:79]
	v_mfma_f32_16x16x32_bf16 v[64:67], v[216:219], v[36:39], v[64:67]
	s_waitcnt lgkmcnt(1)
	v_mfma_f32_16x16x32_bf16 v[32:35], v[72:75], v[32:35], v[76:79]
	s_waitcnt lgkmcnt(0)
	v_mfma_f32_16x16x32_bf16 v[32:35], v[122:125], v[36:39], v[32:35]
	s_setprio 0
	s_and_b64 vcc, exec, s[72:73]
	s_cbranch_vccnz .LBB0_1095
	v_add_u32_e32 v36, v116, v111
	v_cmp_lt_i32_e32 vcc, -1, v36
	s_nop 1
	v_cndmask_b32_e32 v56, v222, v56, vcc
	v_cmp_lt_i32_e32 vcc, 0, v36
	s_nop 1
	v_cndmask_b32_e32 v57, v222, v57, vcc
	v_cmp_lt_i32_e32 vcc, 1, v36
	s_nop 1
	v_cndmask_b32_e32 v58, v222, v58, vcc
	v_cmp_lt_i32_e32 vcc, 2, v36
	s_nop 1
	v_cndmask_b32_e32 v59, v222, v59, vcc
	v_cmp_lt_i32_e32 vcc, 15, v36
	s_nop 1
	v_cndmask_b32_e32 v60, v222, v60, vcc
	v_cmp_lt_i32_e32 vcc, 16, v36
	s_nop 1
	v_cndmask_b32_e32 v61, v222, v61, vcc
	v_cmp_lt_i32_e32 vcc, 17, v36
	s_nop 1
	v_cndmask_b32_e32 v62, v222, v62, vcc
	v_cmp_lt_i32_e32 vcc, 18, v36
	s_nop 1
	v_cndmask_b32_e32 v63, v222, v63, vcc
	v_cmp_lt_i32_e32 vcc, 31, v36
	s_nop 1
	v_cndmask_b32_e32 v64, v222, v64, vcc
	v_cmp_lt_i32_e32 vcc, 32, v36
	s_nop 1
	v_cndmask_b32_e32 v65, v222, v65, vcc
	v_cmp_lt_i32_e32 vcc, 33, v36
	s_nop 1
	v_cndmask_b32_e32 v66, v222, v66, vcc
	v_cmp_lt_i32_e32 vcc, 34, v36
	s_nop 1
	v_cndmask_b32_e32 v67, v222, v67, vcc
	v_cmp_lt_i32_e32 vcc, 47, v36
	s_nop 1
	v_cndmask_b32_e32 v32, v222, v32, vcc
	v_cmp_lt_i32_e32 vcc, 48, v36
	s_nop 1
	v_cndmask_b32_e32 v33, v222, v33, vcc
	v_cmp_lt_i32_e32 vcc, 49, v36
	s_nop 1
	v_cndmask_b32_e32 v34, v222, v34, vcc
	v_cmp_lt_i32_e32 vcc, 50, v36
	s_nop 1
	v_cndmask_b32_e32 v35, v222, v35, vcc
